# v032 + attention: x=0 query-block items published immediately (unblocks the second tile of workgroups 0-7), PV LDS ring fill hoisted above the softplus math, prompt path writes K/V tile to LDS straigh
# baseline (speedup 1.0000x reference)
; __device__ __forceinline__ void attn_phase(const Params& p, LAS unsigned char* lds, int cidx) {
;     ...
;         if (!smp) { const int it = item - 128; x = it >> 6; const int bh = it & 63; b = bh >> 4; h = bh & 15; kt_hi = 4 * x + 3; qrow0 = b * 2048 + x * 256 + 32 * wid; tpos0 = x * 256 + 32 * wid; krow0 = (size_t)b * 2048; cur_pm = b * 8 + x; }
;         else { x = 0; const int bh = item; b = bh >> 4; h = bh & 15; kt_hi = 16; qrow0 = MP + b * 32; tpos0 = 1024; krow0 = 0; cur_pm = 32; }
;     ...
;         if (smp) {
;             asm volatile("s_waitcnt vmcnt(0)" ::: "memory");
;             __syncthreads();
;             if (tid == 0) __hip_atomic_fetch_add(pcnt + 64 * 32, 1u, __ATOMIC_RELAXED, __HIP_MEMORY_SCOPE_AGENT);
;             cur_pm = -1;
;         }
.LBB0_685:
	v_readlane_b32 s32, v234, 57
	s_nop 0
	s_and_b32 s6, s32, 7
	s_cmp_lg_u32 s6, 0
	s_cbranch_scc1 .LBB0_690
	s_waitcnt vmcnt(0)
	s_barrier
	s_and_saveexec_b64 s[2:3], s[16:17]
	s_cbranch_execz .LBB0_689
	s_mov_b64 s[4:5], exec
	v_mbcnt_lo_u32_b32 v1, s4, 0
	v_mbcnt_hi_u32_b32 v1, s5, v1
	v_cmp_eq_u32_e32 vcc, 0, v1
	s_and_b64 s[6:7], exec, vcc
	s_mov_b64 exec, s[6:7]
	s_cbranch_execz .LBB0_689
	s_bcnt1_i32_b64 s4, s[4:5]
	v_mov_b32_e32 v1, s4
	v_readlane_b32 s4, v234, 36
	v_readlane_b32 s5, v234, 37
	s_lshl_b32 s6, s32, 8
	s_add_u32 s4, s4, s6
	s_addc_u32 s5, s5, 0
	s_nop 4
	global_atomic_add v0, v1, s[4:5]
